# v35: P4 last round split into 180 half units (128 rows) with hand-written tile-specialised epilogue; weight conversion moved to workgroups 180-255
# baseline (speedup 1.0000x reference)
.LBB0_388:
	s_add_u32 s8, s26, 0x13200000
	s_addc_u32 s9, s27, 0
	s_add_u32 s10, s26, 0x16400000
	v_readlane_b32 s36, v255, 23
	s_addc_u32 s11, s27, 0
	v_readlane_b32 s50, v255, 37
	v_readlane_b32 s51, v255, 38
	s_add_u32 s12, s50, 0x4200000
	s_addc_u32 s13, s51, 0
	s_add_u32 s14, s50, 0x6200000
	s_addc_u32 s15, s51, 0
	s_add_u32 s16, s50, 0x8200000
	s_addc_u32 s17, s51, 0
	s_add_u32 s18, s50, 0x8300000
	s_addc_u32 s19, s51, 0
	s_add_u32 s20, s50, 0x9500000
	s_addc_u32 s21, s51, 0
	v_readlane_b32 s37, v255, 24
	v_readlane_b32 s38, v255, 25
	v_readlane_b32 s39, v255, 26
	s_add_u32 s36, s50, 0x950e000
	s_addc_u32 s37, s51, 0
	v_and_b32_e32 v15, 15, v0
	v_lshlrev_b32_e32 v16, 1, v13
	v_lshlrev_b32_e32 v18, 2, v0
	s_lshl_b32 s5, s5, 5
	s_mov_b64 s[38:39], 0x80
	v_and_b32_e32 v18, 32, v18
	v_lshl_or_b32 v164, s22, 6, v15
	v_lshl_or_b32 v15, v15, 6, v16
	s_lshl_b32 s7, s22, 13
	s_and_b32 s5, s5, 0x60
	s_add_i32 m0, s75, 0x18000
	v_lshl_add_u64 v[8:9], v[8:9], 0, s[38:39]
	s_ashr_i32 s82, s33, 31
	s_ashr_i32 s83, s24, 31
	v_bitop3_b32 v15, v15, s7, v18 bitop3:0xde
	s_lshl_b32 s7, s5, 7
	s_waitcnt vmcnt(2)
	s_barrier
	global_load_lds_dwordx4 v[8:9], off
	v_lshl_add_u64 v[6:7], v[6:7], 0, s[38:39]
	s_add_i32 m0, s75, 0x1a000
	s_add_i32 s25, s75, 0x8000
	s_add_i32 s69, s75, 0xa000
	global_load_lds_dwordx4 v[6:7], off
	v_lshl_add_u64 v[2:3], v[2:3], 0, s[38:39]
	s_mov_b32 m0, s25
	s_add_u32 s22, s88, 0x40080
	global_load_lds_dwordx4 v[2:3], off
	v_lshl_add_u64 v[2:3], v[4:5], 0, s[38:39]
	s_mov_b32 m0, s69
	s_addc_u32 s23, s89, 0
	global_load_lds_dwordx4 v[2:3], off
	s_add_i32 m0, s75, 0x1c000
	v_lshl_add_u64 v[2:3], s[22:23], 0, v[136:137]
	global_load_lds_dwordx4 v[2:3], off
	v_lshl_add_u64 v[2:3], s[22:23], 0, v[140:141]
	s_add_i32 m0, s75, 0x1e000
	v_lshlrev_b32_e32 v17, 6, v0
	global_load_lds_dwordx4 v[2:3], off
	v_lshlrev_b32_e32 v2, 8, v0
	v_and_b32_e32 v2, 0x18000, v2
	v_lshlrev_b32_e32 v3, 11, v12
	v_or3_b32 v2, v10, v2, v3
	s_movk_i32 s2, 0x3c0
	v_add_u32_e32 v144, v2, v11
	v_lshlrev_b32_e32 v2, 4, v14
	v_readlane_b32 s44, v255, 31
	v_readlane_b32 s45, v255, 32
	v_and_or_b32 v17, v17, s2, v16
	s_waitcnt vmcnt(6)
	s_cmpk_lt_u32 s4, 0x100
	v_and_b32_e32 v2, 0x38000, v2
	v_readlane_b32 s40, v255, 27
	v_readlane_b32 s41, v255, 28
	v_and_b32_e32 v19, 3, v0
	v_bitop3_b32 v165, s7, v17, v18 bitop3:0xf6
	s_cselect_b64 s[44:45], -1, 0
	v_or3_b32 v2, v10, v2, v3
	s_add_i32 s68, 0, 0x10000
	s_add_i32 s28, 0, 0x14000
	s_movk_i32 s52, 0xe800
	s_movk_i32 s64, 0xea00
	v_cmp_eq_u32_e64 s[2:3], 3, v19
	v_or_b32_e32 v166, s5, v13
	v_mov_b32_e32 v145, v143
	v_add_u32_e32 v146, v2, v11
	v_mov_b32_e32 v147, v143
	v_mov_b64_e32 v[148:149], 0x35a
	v_mov_b64_e32 v[150:151], 0x359
	v_add_u32_e32 v167, s68, v165
	v_add_u32_e32 v168, s28, v165
	v_add_u32_e32 v169, 0, v15
	s_movk_i32 s29, 0xe00
	s_movk_i32 s40, 0xc00
	s_movk_i32 s41, 0x1c00
	s_mov_b32 s53, -1
	s_mov_b32 s65, -1
	s_mov_b64 s[80:81], 0x200
	v_mov_b32_e32 v170, 0x3e38aa3b
	v_readlane_b32 s42, v255, 29
	v_readlane_b32 s43, v255, 30
	v_readlane_b32 s46, v255, 33
	v_readlane_b32 s47, v255, 34
	v_readlane_b32 s48, v255, 35
	v_readlane_b32 s49, v255, 36
	s_barrier
	s_mov_b32 s98, 0
	s_branch .LBB0_391

.LBB0_390:
	s_andn2_b64 vcc, exec, s[4:5]
	s_mov_b32 s6, s34
	s_mov_b32 s84, s22
	s_mov_b32 s98, s99
	s_mov_b64 s[88:89], s[54:55]
	s_mov_b64 s[86:87], s[30:31]
	s_cbranch_vccz .LBB0_773
.LBB0_391:
	s_add_i32 s79, s79, 1
	s_mul_i32 s4, s79, s82
	s_mul_hi_u32 s5, s79, s33
	s_add_i32 s5, s5, s4
	s_mul_i32 s4, s79, s33
	s_add_u32 s30, s4, s24
	s_addc_u32 s31, s5, s83
	s_mov_b32 s99, 0
	s_cmp_eq_u32 s79, 3
	s_cbranch_scc0 .Lp4_full_next
	s_lshr_b32 s30, s24, 1
	s_addk_i32 s30, 0x300
	s_mov_b32 s31, 0
	s_and_b32 s99, s24, 1
	s_or_b32 s99, s99, 2
	s_cmpk_lt_u32 s24, 180
	s_cbranch_scc1 .Lp4_full_next
	s_movk_i32 s30, 0x7fff
.Lp4_full_next:
	v_cmp_gt_i64_e32 vcc, s[30:31], v[150:151]
	v_cmp_lt_i64_e64 s[4:5], s[30:31], v[148:149]
	s_cbranch_vccnz .LBB0_397
	s_ashr_i32 s7, s30, 31
	s_lshr_b32 s7, s7, 29
	s_add_i32 s7, s30, s7
	s_and_b32 s22, s7, -8
	s_sub_i32 s30, s30, s22
	s_cmp_gt_i32 s30, 1
	s_mov_b64 s[22:23], -1
	s_cbranch_scc0 .LBB0_394
	s_mul_i32 s22, s30, 0x6b
	s_add_i32 s31, s22, 2
	s_mov_b64 s[22:23], 0

.LBB0_397:
	s_ashr_i32 s23, s22, 31
	s_lshl_b64 s[30:31], s[22:23], 19
	s_add_u32 s30, s70, s30
	s_addc_u32 s31, s71, s31
	s_and_b32 s100, s99, 1
	s_lshl_b32 s100, s100, 18
	s_add_u32 s30, s30, s100
	s_addc_u32 s31, s31, 0
	s_and_b64 s[46:47], s[4:5], exec
	s_cselect_b32 s7, s31, s87
	s_cselect_b32 s23, s30, s86
	s_ashr_i32 s35, s34, 31
	s_lshl_b64 s[46:47], s[34:35], 19
	s_add_u32 s54, s72, s46
	s_addc_u32 s55, s73, s47
	s_and_b64 s[46:47], s[4:5], exec
	s_cselect_b32 s35, s55, s89
	s_cselect_b32 s46, s54, s88
	s_add_u32 s86, s86, 0x40080
	s_addc_u32 s87, s87, 0
	s_add_u32 s47, s88, 0x100
	v_mov_b32_e32 v2, 0
	s_mov_b64 s[42:43], s[90:91]
	s_addc_u32 s48, s89, 0
	s_mov_b32 s49, -2
	v_mov_b32_e32 v3, v2
	v_mov_b32_e32 v4, v2
	v_mov_b32_e32 v5, v2
	v_mov_b32_e32 v6, v2
	v_mov_b32_e32 v7, v2
	v_mov_b32_e32 v8, v2
	v_mov_b32_e32 v9, v2
	v_mov_b32_e32 v18, v2
	v_mov_b32_e32 v19, v2
	v_mov_b32_e32 v20, v2
	v_mov_b32_e32 v21, v2
	v_mov_b32_e32 v22, v2
	v_mov_b32_e32 v23, v2
	v_mov_b32_e32 v24, v2
	v_mov_b32_e32 v25, v2
	v_mov_b32_e32 v34, v2
	v_mov_b32_e32 v35, v2
	v_mov_b32_e32 v36, v2
	v_mov_b32_e32 v37, v2
	v_mov_b32_e32 v38, v2
	v_mov_b32_e32 v39, v2
	v_mov_b32_e32 v40, v2
	v_mov_b32_e32 v41, v2
	v_mov_b32_e32 v50, v2
	v_mov_b32_e32 v51, v2
	v_mov_b32_e32 v52, v2
	v_mov_b32_e32 v53, v2
	v_mov_b32_e32 v54, v2
	v_mov_b32_e32 v55, v2
	v_mov_b32_e32 v56, v2
	v_mov_b32_e32 v57, v2
	v_mov_b32_e32 v10, v2
	v_mov_b32_e32 v11, v2
	v_mov_b32_e32 v12, v2
	v_mov_b32_e32 v13, v2
	v_mov_b32_e32 v14, v2
	v_mov_b32_e32 v15, v2
	v_mov_b32_e32 v16, v2
	v_mov_b32_e32 v17, v2
	v_mov_b32_e32 v26, v2
	v_mov_b32_e32 v27, v2
	v_mov_b32_e32 v28, v2
	v_mov_b32_e32 v29, v2
	v_mov_b32_e32 v30, v2
	v_mov_b32_e32 v31, v2
	v_mov_b32_e32 v32, v2
	v_mov_b32_e32 v33, v2
	v_mov_b32_e32 v42, v2
	v_mov_b32_e32 v43, v2
	v_mov_b32_e32 v44, v2
	v_mov_b32_e32 v45, v2
	v_mov_b32_e32 v46, v2
	v_mov_b32_e32 v47, v2
	v_mov_b32_e32 v48, v2
	v_mov_b32_e32 v49, v2
	v_mov_b32_e32 v58, v2
	v_mov_b32_e32 v59, v2
	v_mov_b32_e32 v60, v2
	v_mov_b32_e32 v61, v2
	v_mov_b32_e32 v62, v2
	v_mov_b32_e32 v63, v2
	v_mov_b32_e32 v64, v2
	v_mov_b32_e32 v65, v2
	v_mov_b32_e32 v66, v2
	v_mov_b32_e32 v67, v2
	v_mov_b32_e32 v68, v2
	v_mov_b32_e32 v69, v2
	v_mov_b32_e32 v70, v2
	v_mov_b32_e32 v71, v2
	v_mov_b32_e32 v72, v2
	v_mov_b32_e32 v73, v2
	v_mov_b32_e32 v82, v2
	v_mov_b32_e32 v83, v2
	v_mov_b32_e32 v84, v2
	v_mov_b32_e32 v85, v2
	v_mov_b32_e32 v86, v2
	v_mov_b32_e32 v87, v2
	v_mov_b32_e32 v88, v2
	v_mov_b32_e32 v89, v2
	v_mov_b32_e32 v98, v2
	v_mov_b32_e32 v99, v2
	v_mov_b32_e32 v100, v2
	v_mov_b32_e32 v101, v2
	v_mov_b32_e32 v102, v2
	v_mov_b32_e32 v103, v2
	v_mov_b32_e32 v104, v2
	v_mov_b32_e32 v105, v2
	v_mov_b32_e32 v114, v2
	v_mov_b32_e32 v115, v2
	v_mov_b32_e32 v116, v2
	v_mov_b32_e32 v117, v2
	v_mov_b32_e32 v118, v2
	v_mov_b32_e32 v119, v2
	v_mov_b32_e32 v120, v2
	v_mov_b32_e32 v121, v2
	v_mov_b32_e32 v74, v2
	v_mov_b32_e32 v75, v2
	v_mov_b32_e32 v76, v2
	v_mov_b32_e32 v77, v2
	v_mov_b32_e32 v78, v2
	v_mov_b32_e32 v79, v2
	v_mov_b32_e32 v80, v2
	v_mov_b32_e32 v81, v2
	v_mov_b32_e32 v90, v2
	v_mov_b32_e32 v91, v2
	v_mov_b32_e32 v92, v2
	v_mov_b32_e32 v93, v2
	v_mov_b32_e32 v94, v2
	v_mov_b32_e32 v95, v2
	v_mov_b32_e32 v96, v2
	v_mov_b32_e32 v97, v2
	v_mov_b32_e32 v106, v2
	v_mov_b32_e32 v107, v2
	v_mov_b32_e32 v108, v2
	v_mov_b32_e32 v109, v2
	v_mov_b32_e32 v110, v2
	v_mov_b32_e32 v111, v2
	v_mov_b32_e32 v112, v2
	v_mov_b32_e32 v113, v2
	v_mov_b32_e32 v122, v2
	v_mov_b32_e32 v123, v2
	v_mov_b32_e32 v124, v2
	v_mov_b32_e32 v125, v2
	v_mov_b32_e32 v126, v2
	v_mov_b32_e32 v127, v2
	v_mov_b32_e32 v128, v2
	v_mov_b32_e32 v129, v2
	s_bitcmp1_b32 s98, 1
	s_cbranch_scc1 .Lk4h_loop

.Lk4_after:
	s_and_b64 vcc, exec, s[44:45]
	s_cbranch_vccz .LBB0_401
	s_barrier
.LBB0_401:
	s_nop 7
	v_lshl_add_u32 v152, s84, 8, v164
	v_mov_b32_e32 v171, v170
	s_bitcmp1_b32 s98, 1
	s_cbranch_scc1 .Lepi_half
	s_lshl_b32 s46, s6, 9
	s_cmp_gt_i32 s6, 5
	s_cbranch_scc1 .Lepi_pr
	v_mul_u32_u24_e32 v153, 0xc00, v152
	v_lshl_add_u32 v153, v166, 1, v153
	s_add_u32 s86, s8, s46
	s_addc_u32 s87, s9, 0
	s_cmp_lt_i32 s6, 2
	s_cbranch_scc0 .Lepi_kv
	v_pk_mul_f32 v[126:127], v[126:127], v[170:171]
	v_pk_mul_f32 v[128:129], v[128:129], v[170:171]
	v_pk_mul_f32 v[122:123], v[122:123], v[170:171]
	v_pk_mul_f32 v[124:125], v[124:125], v[170:171]
	v_cvt_pk_bf16_f32 v172, v126, v127
	v_cvt_pk_bf16_f32 v173, v128, v129
	v_cvt_pk_bf16_f32 v174, v122, v123
	v_cvt_pk_bf16_f32 v175, v124, v125
	global_store_dwordx4 v153, v[172:175], s[86:87] offset:0
	v_pk_mul_f32 v[118:119], v[118:119], v[170:171]
	v_pk_mul_f32 v[120:121], v[120:121], v[170:171]
	v_pk_mul_f32 v[114:115], v[114:115], v[170:171]
	v_pk_mul_f32 v[116:117], v[116:117], v[170:171]
	v_cvt_pk_bf16_f32 v176, v118, v119
	v_cvt_pk_bf16_f32 v177, v120, v121
	v_cvt_pk_bf16_f32 v178, v114, v115
	v_cvt_pk_bf16_f32 v179, v116, v117
	global_store_dwordx4 v153, v[176:179], s[86:87] offset:256
	s_add_u32 s86, s86, 0xc000
	s_addc_u32 s87, s87, 0
	v_pk_mul_f32 v[110:111], v[110:111], v[170:171]
	v_pk_mul_f32 v[112:113], v[112:113], v[170:171]
	v_pk_mul_f32 v[106:107], v[106:107], v[170:171]
	v_pk_mul_f32 v[108:109], v[108:109], v[170:171]
	v_cvt_pk_bf16_f32 v180, v110, v111
	v_cvt_pk_bf16_f32 v181, v112, v113
	v_cvt_pk_bf16_f32 v182, v106, v107
	v_cvt_pk_bf16_f32 v183, v108, v109
	global_store_dwordx4 v153, v[180:183], s[86:87] offset:0
	v_pk_mul_f32 v[102:103], v[102:103], v[170:171]
	v_pk_mul_f32 v[104:105], v[104:105], v[170:171]
	v_pk_mul_f32 v[98:99], v[98:99], v[170:171]
	v_pk_mul_f32 v[100:101], v[100:101], v[170:171]
	v_cvt_pk_bf16_f32 v184, v102, v103
	v_cvt_pk_bf16_f32 v185, v104, v105
	v_cvt_pk_bf16_f32 v186, v98, v99
	v_cvt_pk_bf16_f32 v187, v100, v101
	global_store_dwordx4 v153, v[184:187], s[86:87] offset:256
	s_add_u32 s86, s86, 0xc000
	s_addc_u32 s87, s87, 0
	v_pk_mul_f32 v[94:95], v[94:95], v[170:171]
	v_pk_mul_f32 v[96:97], v[96:97], v[170:171]
	v_pk_mul_f32 v[90:91], v[90:91], v[170:171]
	v_pk_mul_f32 v[92:93], v[92:93], v[170:171]
	v_cvt_pk_bf16_f32 v172, v94, v95
	v_cvt_pk_bf16_f32 v173, v96, v97
	v_cvt_pk_bf16_f32 v174, v90, v91
	v_cvt_pk_bf16_f32 v175, v92, v93
	global_store_dwordx4 v153, v[172:175], s[86:87] offset:0
	v_pk_mul_f32 v[86:87], v[86:87], v[170:171]
	v_pk_mul_f32 v[88:89], v[88:89], v[170:171]
	v_pk_mul_f32 v[82:83], v[82:83], v[170:171]
	v_pk_mul_f32 v[84:85], v[84:85], v[170:171]
	v_cvt_pk_bf16_f32 v176, v86, v87
	v_cvt_pk_bf16_f32 v177, v88, v89
	v_cvt_pk_bf16_f32 v178, v82, v83
	v_cvt_pk_bf16_f32 v179, v84, v85
	global_store_dwordx4 v153, v[176:179], s[86:87] offset:256
	s_add_u32 s86, s86, 0xc000
	s_addc_u32 s87, s87, 0
	v_pk_mul_f32 v[78:79], v[78:79], v[170:171]
	v_pk_mul_f32 v[80:81], v[80:81], v[170:171]
	v_pk_mul_f32 v[74:75], v[74:75], v[170:171]
	v_pk_mul_f32 v[76:77], v[76:77], v[170:171]
	v_cvt_pk_bf16_f32 v180, v78, v79
	v_cvt_pk_bf16_f32 v181, v80, v81
	v_cvt_pk_bf16_f32 v182, v74, v75
	v_cvt_pk_bf16_f32 v183, v76, v77
	global_store_dwordx4 v153, v[180:183], s[86:87] offset:0
	v_pk_mul_f32 v[70:71], v[70:71], v[170:171]
	v_pk_mul_f32 v[72:73], v[72:73], v[170:171]
	v_pk_mul_f32 v[66:67], v[66:67], v[170:171]
	v_pk_mul_f32 v[68:69], v[68:69], v[170:171]
	v_cvt_pk_bf16_f32 v184, v70, v71
	v_cvt_pk_bf16_f32 v185, v72, v73
	v_cvt_pk_bf16_f32 v186, v66, v67
	v_cvt_pk_bf16_f32 v187, v68, v69
	global_store_dwordx4 v153, v[184:187], s[86:87] offset:256
	s_add_u32 s86, s86, 0x3c000
	s_addc_u32 s87, s87, 0
	v_pk_mul_f32 v[62:63], v[62:63], v[170:171]
	v_pk_mul_f32 v[64:65], v[64:65], v[170:171]
	v_pk_mul_f32 v[58:59], v[58:59], v[170:171]
	v_pk_mul_f32 v[60:61], v[60:61], v[170:171]
	v_cvt_pk_bf16_f32 v172, v62, v63
	v_cvt_pk_bf16_f32 v173, v64, v65
	v_cvt_pk_bf16_f32 v174, v58, v59
	v_cvt_pk_bf16_f32 v175, v60, v61
	global_store_dwordx4 v153, v[172:175], s[86:87] offset:0
	v_pk_mul_f32 v[54:55], v[54:55], v[170:171]
	v_pk_mul_f32 v[56:57], v[56:57], v[170:171]
	v_pk_mul_f32 v[50:51], v[50:51], v[170:171]
	v_pk_mul_f32 v[52:53], v[52:53], v[170:171]
	v_cvt_pk_bf16_f32 v176, v54, v55
	v_cvt_pk_bf16_f32 v177, v56, v57
	v_cvt_pk_bf16_f32 v178, v50, v51
	v_cvt_pk_bf16_f32 v179, v52, v53
	global_store_dwordx4 v153, v[176:179], s[86:87] offset:256
	s_add_u32 s86, s86, 0xc000
	s_addc_u32 s87, s87, 0
	v_pk_mul_f32 v[46:47], v[46:47], v[170:171]
	v_pk_mul_f32 v[48:49], v[48:49], v[170:171]
	v_pk_mul_f32 v[42:43], v[42:43], v[170:171]
	v_pk_mul_f32 v[44:45], v[44:45], v[170:171]
	v_cvt_pk_bf16_f32 v180, v46, v47
	v_cvt_pk_bf16_f32 v181, v48, v49
	v_cvt_pk_bf16_f32 v182, v42, v43
	v_cvt_pk_bf16_f32 v183, v44, v45
	global_store_dwordx4 v153, v[180:183], s[86:87] offset:0
	v_pk_mul_f32 v[38:39], v[38:39], v[170:171]
	v_pk_mul_f32 v[40:41], v[40:41], v[170:171]
	v_pk_mul_f32 v[34:35], v[34:35], v[170:171]
	v_pk_mul_f32 v[36:37], v[36:37], v[170:171]
	v_cvt_pk_bf16_f32 v184, v38, v39
	v_cvt_pk_bf16_f32 v185, v40, v41
	v_cvt_pk_bf16_f32 v186, v34, v35
	v_cvt_pk_bf16_f32 v187, v36, v37
	global_store_dwordx4 v153, v[184:187], s[86:87] offset:256
	s_add_u32 s86, s86, 0xc000
	s_addc_u32 s87, s87, 0
	v_pk_mul_f32 v[30:31], v[30:31], v[170:171]
	v_pk_mul_f32 v[32:33], v[32:33], v[170:171]
	v_pk_mul_f32 v[26:27], v[26:27], v[170:171]
	v_pk_mul_f32 v[28:29], v[28:29], v[170:171]
	v_cvt_pk_bf16_f32 v172, v30, v31
	v_cvt_pk_bf16_f32 v173, v32, v33
	v_cvt_pk_bf16_f32 v174, v26, v27
	v_cvt_pk_bf16_f32 v175, v28, v29
	global_store_dwordx4 v153, v[172:175], s[86:87] offset:0
	v_pk_mul_f32 v[22:23], v[22:23], v[170:171]
	v_pk_mul_f32 v[24:25], v[24:25], v[170:171]
	v_pk_mul_f32 v[18:19], v[18:19], v[170:171]
	v_pk_mul_f32 v[20:21], v[20:21], v[170:171]
	v_cvt_pk_bf16_f32 v176, v22, v23
	v_cvt_pk_bf16_f32 v177, v24, v25
	v_cvt_pk_bf16_f32 v178, v18, v19
	v_cvt_pk_bf16_f32 v179, v20, v21
	global_store_dwordx4 v153, v[176:179], s[86:87] offset:256
	s_add_u32 s86, s86, 0xc000
	s_addc_u32 s87, s87, 0
	v_pk_mul_f32 v[14:15], v[14:15], v[170:171]
	v_pk_mul_f32 v[16:17], v[16:17], v[170:171]
	v_pk_mul_f32 v[10:11], v[10:11], v[170:171]
	v_pk_mul_f32 v[12:13], v[12:13], v[170:171]
	v_cvt_pk_bf16_f32 v180, v14, v15
	v_cvt_pk_bf16_f32 v181, v16, v17
	v_cvt_pk_bf16_f32 v182, v10, v11
	v_cvt_pk_bf16_f32 v183, v12, v13
	global_store_dwordx4 v153, v[180:183], s[86:87] offset:0
	v_pk_mul_f32 v[6:7], v[6:7], v[170:171]
	v_pk_mul_f32 v[8:9], v[8:9], v[170:171]
	v_pk_mul_f32 v[2:3], v[2:3], v[170:171]
	v_pk_mul_f32 v[4:5], v[4:5], v[170:171]
	v_cvt_pk_bf16_f32 v184, v6, v7
	v_cvt_pk_bf16_f32 v185, v8, v9
	v_cvt_pk_bf16_f32 v186, v2, v3
	v_cvt_pk_bf16_f32 v187, v4, v5
	global_store_dwordx4 v153, v[184:187], s[86:87] offset:256
	s_branch .Lepi_done

.Lepi_prs:
	v_add_u32_e32 v157, 0xffffc000, v152
	v_lshrrev_b32_e32 v157, 2, v157
	v_mul_u32_u24_e32 v157, 0x1c00, v157
	v_add_u32_e32 v156, v156, v157
	s_add_u32 s88, s36, s46
	s_addc_u32 s89, s37, 0
	s_sub_u32 s88, s88, 0x1800
	s_subb_u32 s89, s89, 0
	v_cvt_pk_bf16_f32 v172, v126, v127
	v_cvt_pk_bf16_f32 v173, v128, v129
	v_cvt_pk_bf16_f32 v174, v122, v123
	v_cvt_pk_bf16_f32 v175, v124, v125
	global_store_dwordx4 v153, v[172:175], s[86:87] offset:0
	v_cvt_pk_bf16_f32 v176, v118, v119
	v_cvt_pk_bf16_f32 v177, v120, v121
	v_cvt_pk_bf16_f32 v178, v114, v115
	v_cvt_pk_bf16_f32 v179, v116, v117
	global_store_dwordx4 v153, v[176:179], s[86:87] offset:256
	s_mov_b64 exec, s[2:3]
	global_store_dwordx4 v156, v[126:129], s[88:89] offset:0
	global_store_dwordx4 v156, v[122:125], s[88:89] offset:16
	global_store_dwordx4 v156, v[118:121], s[88:89] offset:512
	global_store_dwordx4 v156, v[114:117], s[88:89] offset:528
	s_mov_b64 exec, -1
	s_add_u32 s86, s86, 0xe000
	s_addc_u32 s87, s87, 0
	s_add_u32 s88, s88, 0x7000
	s_addc_u32 s89, s89, 0
	v_cvt_pk_bf16_f32 v180, v110, v111
	v_cvt_pk_bf16_f32 v181, v112, v113
	v_cvt_pk_bf16_f32 v182, v106, v107
	v_cvt_pk_bf16_f32 v183, v108, v109
	global_store_dwordx4 v153, v[180:183], s[86:87] offset:0
	v_cvt_pk_bf16_f32 v184, v102, v103
	v_cvt_pk_bf16_f32 v185, v104, v105
	v_cvt_pk_bf16_f32 v186, v98, v99
	v_cvt_pk_bf16_f32 v187, v100, v101
	global_store_dwordx4 v153, v[184:187], s[86:87] offset:256
	s_mov_b64 exec, s[2:3]
	global_store_dwordx4 v156, v[110:113], s[88:89] offset:0
	global_store_dwordx4 v156, v[106:109], s[88:89] offset:16
	global_store_dwordx4 v156, v[102:105], s[88:89] offset:512
	global_store_dwordx4 v156, v[98:101], s[88:89] offset:528
	s_mov_b64 exec, -1
	s_add_u32 s86, s86, 0xe000
	s_addc_u32 s87, s87, 0
	s_add_u32 s88, s88, 0x7000
	s_addc_u32 s89, s89, 0
	v_cvt_pk_bf16_f32 v172, v94, v95
	v_cvt_pk_bf16_f32 v173, v96, v97
	v_cvt_pk_bf16_f32 v174, v90, v91
	v_cvt_pk_bf16_f32 v175, v92, v93
	global_store_dwordx4 v153, v[172:175], s[86:87] offset:0
	v_cvt_pk_bf16_f32 v176, v86, v87
	v_cvt_pk_bf16_f32 v177, v88, v89
	v_cvt_pk_bf16_f32 v178, v82, v83
	v_cvt_pk_bf16_f32 v179, v84, v85
	global_store_dwordx4 v153, v[176:179], s[86:87] offset:256
	s_mov_b64 exec, s[2:3]
	global_store_dwordx4 v156, v[94:97], s[88:89] offset:0
	global_store_dwordx4 v156, v[90:93], s[88:89] offset:16
	global_store_dwordx4 v156, v[86:89], s[88:89] offset:512
	global_store_dwordx4 v156, v[82:85], s[88:89] offset:528
	s_mov_b64 exec, -1
	s_add_u32 s86, s86, 0xe000
	s_addc_u32 s87, s87, 0
	s_add_u32 s88, s88, 0x7000
	s_addc_u32 s89, s89, 0
	v_cvt_pk_bf16_f32 v180, v78, v79
	v_cvt_pk_bf16_f32 v181, v80, v81
	v_cvt_pk_bf16_f32 v182, v74, v75
	v_cvt_pk_bf16_f32 v183, v76, v77
	global_store_dwordx4 v153, v[180:183], s[86:87] offset:0
	v_cvt_pk_bf16_f32 v184, v70, v71
	v_cvt_pk_bf16_f32 v185, v72, v73
	v_cvt_pk_bf16_f32 v186, v66, v67
	v_cvt_pk_bf16_f32 v187, v68, v69
	global_store_dwordx4 v153, v[184:187], s[86:87] offset:256
	s_mov_b64 exec, s[2:3]
	global_store_dwordx4 v156, v[78:81], s[88:89] offset:0
	global_store_dwordx4 v156, v[74:77], s[88:89] offset:16
	global_store_dwordx4 v156, v[70:73], s[88:89] offset:512
	global_store_dwordx4 v156, v[66:69], s[88:89] offset:528
	s_mov_b64 exec, -1
	s_add_u32 s86, s86, 0x46000
	s_addc_u32 s87, s87, 0
	s_add_u32 s88, s88, 0x23000
	s_addc_u32 s89, s89, 0
	v_cvt_pk_bf16_f32 v172, v62, v63
	v_cvt_pk_bf16_f32 v173, v64, v65
	v_cvt_pk_bf16_f32 v174, v58, v59
	v_cvt_pk_bf16_f32 v175, v60, v61
	global_store_dwordx4 v153, v[172:175], s[86:87] offset:0
	v_cvt_pk_bf16_f32 v176, v54, v55
	v_cvt_pk_bf16_f32 v177, v56, v57
	v_cvt_pk_bf16_f32 v178, v50, v51
	v_cvt_pk_bf16_f32 v179, v52, v53
	global_store_dwordx4 v153, v[176:179], s[86:87] offset:256
	s_mov_b64 exec, s[2:3]
	global_store_dwordx4 v156, v[62:65], s[88:89] offset:0
	global_store_dwordx4 v156, v[58:61], s[88:89] offset:16
	global_store_dwordx4 v156, v[54:57], s[88:89] offset:512
	global_store_dwordx4 v156, v[50:53], s[88:89] offset:528
	s_mov_b64 exec, -1
	s_add_u32 s86, s86, 0xe000
	s_addc_u32 s87, s87, 0
	s_add_u32 s88, s88, 0x7000
	s_addc_u32 s89, s89, 0
	v_cvt_pk_bf16_f32 v180, v46, v47
	v_cvt_pk_bf16_f32 v181, v48, v49
	v_cvt_pk_bf16_f32 v182, v42, v43
	v_cvt_pk_bf16_f32 v183, v44, v45
	global_store_dwordx4 v153, v[180:183], s[86:87] offset:0
	v_cvt_pk_bf16_f32 v184, v38, v39
	v_cvt_pk_bf16_f32 v185, v40, v41
	v_cvt_pk_bf16_f32 v186, v34, v35
	v_cvt_pk_bf16_f32 v187, v36, v37
	global_store_dwordx4 v153, v[184:187], s[86:87] offset:256
	s_mov_b64 exec, s[2:3]
	global_store_dwordx4 v156, v[46:49], s[88:89] offset:0
	global_store_dwordx4 v156, v[42:45], s[88:89] offset:16
	global_store_dwordx4 v156, v[38:41], s[88:89] offset:512
	global_store_dwordx4 v156, v[34:37], s[88:89] offset:528
	s_mov_b64 exec, -1
	s_add_u32 s86, s86, 0xe000
	s_addc_u32 s87, s87, 0
	s_add_u32 s88, s88, 0x7000
	s_addc_u32 s89, s89, 0
	v_cvt_pk_bf16_f32 v172, v30, v31
	v_cvt_pk_bf16_f32 v173, v32, v33
	v_cvt_pk_bf16_f32 v174, v26, v27
	v_cvt_pk_bf16_f32 v175, v28, v29
	global_store_dwordx4 v153, v[172:175], s[86:87] offset:0
	v_cvt_pk_bf16_f32 v176, v22, v23
	v_cvt_pk_bf16_f32 v177, v24, v25
	v_cvt_pk_bf16_f32 v178, v18, v19
	v_cvt_pk_bf16_f32 v179, v20, v21
	global_store_dwordx4 v153, v[176:179], s[86:87] offset:256
	s_mov_b64 exec, s[2:3]
	global_store_dwordx4 v156, v[30:33], s[88:89] offset:0
	global_store_dwordx4 v156, v[26:29], s[88:89] offset:16
	global_store_dwordx4 v156, v[22:25], s[88:89] offset:512
	global_store_dwordx4 v156, v[18:21], s[88:89] offset:528
	s_mov_b64 exec, -1
	s_add_u32 s86, s86, 0xe000
	s_addc_u32 s87, s87, 0
	s_add_u32 s88, s88, 0x7000
	s_addc_u32 s89, s89, 0
	v_cvt_pk_bf16_f32 v180, v14, v15
	v_cvt_pk_bf16_f32 v181, v16, v17
	v_cvt_pk_bf16_f32 v182, v10, v11
	v_cvt_pk_bf16_f32 v183, v12, v13
	global_store_dwordx4 v153, v[180:183], s[86:87] offset:0
	v_cvt_pk_bf16_f32 v184, v6, v7
	v_cvt_pk_bf16_f32 v185, v8, v9
	v_cvt_pk_bf16_f32 v186, v2, v3
	v_cvt_pk_bf16_f32 v187, v4, v5
	global_store_dwordx4 v153, v[184:187], s[86:87] offset:256
	s_mov_b64 exec, s[2:3]
	global_store_dwordx4 v156, v[14:17], s[88:89] offset:0
	global_store_dwordx4 v156, v[10:13], s[88:89] offset:16
	global_store_dwordx4 v156, v[6:9], s[88:89] offset:512
	global_store_dwordx4 v156, v[2:5], s[88:89] offset:528
	s_mov_b64 exec, -1
	s_branch .Lepi_done
.Lepi_half:
	s_and_b32 s46, s98, 1
	s_lshl_b32 s46, s46, 7
	v_add_u32_e32 v152, s46, v152
	s_lshl_b32 s46, s6, 9
	s_cmp_gt_i32 s6, 5
	s_cbranch_scc1 .Lepi_pr_h
	v_mul_u32_u24_e32 v153, 0xc00, v152
	v_lshl_add_u32 v153, v166, 1, v153
	s_add_u32 s86, s8, s46
	s_addc_u32 s87, s9, 0
	s_cmp_lt_i32 s6, 2
	s_cbranch_scc0 .Lepi_kv_h
	v_pk_mul_f32 v[126:127], v[126:127], v[170:171]
	v_pk_mul_f32 v[128:129], v[128:129], v[170:171]
	v_pk_mul_f32 v[122:123], v[122:123], v[170:171]
	v_pk_mul_f32 v[124:125], v[124:125], v[170:171]
	v_cvt_pk_bf16_f32 v172, v126, v127
	v_cvt_pk_bf16_f32 v173, v128, v129
	v_cvt_pk_bf16_f32 v174, v122, v123
	v_cvt_pk_bf16_f32 v175, v124, v125
	global_store_dwordx4 v153, v[172:175], s[86:87] offset:0
	v_pk_mul_f32 v[118:119], v[118:119], v[170:171]
	v_pk_mul_f32 v[120:121], v[120:121], v[170:171]
	v_pk_mul_f32 v[114:115], v[114:115], v[170:171]
	v_pk_mul_f32 v[116:117], v[116:117], v[170:171]
	v_cvt_pk_bf16_f32 v176, v118, v119
	v_cvt_pk_bf16_f32 v177, v120, v121
	v_cvt_pk_bf16_f32 v178, v114, v115
	v_cvt_pk_bf16_f32 v179, v116, v117
	global_store_dwordx4 v153, v[176:179], s[86:87] offset:256
	s_add_u32 s86, s86, 0xc000
	s_addc_u32 s87, s87, 0
	v_pk_mul_f32 v[110:111], v[110:111], v[170:171]
	v_pk_mul_f32 v[112:113], v[112:113], v[170:171]
	v_pk_mul_f32 v[106:107], v[106:107], v[170:171]
	v_pk_mul_f32 v[108:109], v[108:109], v[170:171]
	v_cvt_pk_bf16_f32 v180, v110, v111
	v_cvt_pk_bf16_f32 v181, v112, v113
	v_cvt_pk_bf16_f32 v182, v106, v107
	v_cvt_pk_bf16_f32 v183, v108, v109
	global_store_dwordx4 v153, v[180:183], s[86:87] offset:0
	v_pk_mul_f32 v[102:103], v[102:103], v[170:171]
	v_pk_mul_f32 v[104:105], v[104:105], v[170:171]
	v_pk_mul_f32 v[98:99], v[98:99], v[170:171]
	v_pk_mul_f32 v[100:101], v[100:101], v[170:171]
	v_cvt_pk_bf16_f32 v184, v102, v103
	v_cvt_pk_bf16_f32 v185, v104, v105
	v_cvt_pk_bf16_f32 v186, v98, v99
	v_cvt_pk_bf16_f32 v187, v100, v101
	global_store_dwordx4 v153, v[184:187], s[86:87] offset:256
	s_add_u32 s86, s86, 0xc000
	s_addc_u32 s87, s87, 0
	v_pk_mul_f32 v[94:95], v[94:95], v[170:171]
	v_pk_mul_f32 v[96:97], v[96:97], v[170:171]
	v_pk_mul_f32 v[90:91], v[90:91], v[170:171]
	v_pk_mul_f32 v[92:93], v[92:93], v[170:171]
	v_cvt_pk_bf16_f32 v172, v94, v95
	v_cvt_pk_bf16_f32 v173, v96, v97
	v_cvt_pk_bf16_f32 v174, v90, v91
	v_cvt_pk_bf16_f32 v175, v92, v93
	global_store_dwordx4 v153, v[172:175], s[86:87] offset:0
	v_pk_mul_f32 v[86:87], v[86:87], v[170:171]
	v_pk_mul_f32 v[88:89], v[88:89], v[170:171]
	v_pk_mul_f32 v[82:83], v[82:83], v[170:171]
	v_pk_mul_f32 v[84:85], v[84:85], v[170:171]
	v_cvt_pk_bf16_f32 v176, v86, v87
	v_cvt_pk_bf16_f32 v177, v88, v89
	v_cvt_pk_bf16_f32 v178, v82, v83
	v_cvt_pk_bf16_f32 v179, v84, v85
	global_store_dwordx4 v153, v[176:179], s[86:87] offset:256
	s_add_u32 s86, s86, 0xc000
	s_addc_u32 s87, s87, 0
	v_pk_mul_f32 v[78:79], v[78:79], v[170:171]
	v_pk_mul_f32 v[80:81], v[80:81], v[170:171]
	v_pk_mul_f32 v[74:75], v[74:75], v[170:171]
	v_pk_mul_f32 v[76:77], v[76:77], v[170:171]
	v_cvt_pk_bf16_f32 v180, v78, v79
	v_cvt_pk_bf16_f32 v181, v80, v81
	v_cvt_pk_bf16_f32 v182, v74, v75
	v_cvt_pk_bf16_f32 v183, v76, v77
	global_store_dwordx4 v153, v[180:183], s[86:87] offset:0
	v_pk_mul_f32 v[70:71], v[70:71], v[170:171]
	v_pk_mul_f32 v[72:73], v[72:73], v[170:171]
	v_pk_mul_f32 v[66:67], v[66:67], v[170:171]
	v_pk_mul_f32 v[68:69], v[68:69], v[170:171]
	v_cvt_pk_bf16_f32 v184, v70, v71
	v_cvt_pk_bf16_f32 v185, v72, v73
	v_cvt_pk_bf16_f32 v186, v66, v67
	v_cvt_pk_bf16_f32 v187, v68, v69
	global_store_dwordx4 v153, v[184:187], s[86:87] offset:256
	s_branch .Lepi_done
.Lepi_kv_h:
	s_cmp_gt_u32 s6, 3
	s_cselect_b32 s88, s14, s12
	s_cselect_b32 s89, s15, s13
	s_cselect_b32 s48, s18, s16
	s_cselect_b32 s49, s19, s17
	s_cmp_gt_i32 s84, 63
	s_cselect_b32 s88, s48, s88
	s_cselect_b32 s89, s49, s89
	s_cselect_b32 s48, 0x2000000, 0
	s_sub_u32 s88, s88, s48
	s_subb_u32 s89, s89, 0
	s_and_b32 s48, s6, 1
	s_lshl_b32 s48, s48, 10
	s_add_u32 s88, s88, s48
	s_addc_u32 s89, s89, 0
	v_lshlrev_b32_e32 v154, 11, v152
	v_lshl_add_u32 v154, v166, 2, v154
	v_and_b32_e32 v157, 8, v164
	v_mul_u32_u24_e32 v157, 0x7fe, v157
	v_sub_u32_e32 v154, v154, v157
	v_add_u32_e32 v155, 0x4000, v154
	v_cvt_pk_bf16_f32 v172, v126, v127
	v_cvt_pk_bf16_f32 v173, v128, v129
	v_cvt_pk_bf16_f32 v174, v122, v123
	v_cvt_pk_bf16_f32 v175, v124, v125
	global_store_dwordx4 v153, v[172:175], s[86:87] offset:0
	v_mov_b32_e32 v188, v126
	v_mov_b32_e32 v189, v127
	v_mov_b32_e32 v190, v128
	v_mov_b32_e32 v191, v129
	v_mov_b32_dpp v126, v122 row_ror:8 row_mask:0xf bank_mask:0xc
	v_mov_b32_dpp v127, v123 row_ror:8 row_mask:0xf bank_mask:0xc
	v_mov_b32_dpp v128, v124 row_ror:8 row_mask:0xf bank_mask:0xc
	v_mov_b32_dpp v129, v125 row_ror:8 row_mask:0xf bank_mask:0xc
	v_mov_b32_dpp v122, v188 row_ror:8 row_mask:0xf bank_mask:0x3
	v_mov_b32_dpp v123, v189 row_ror:8 row_mask:0xf bank_mask:0x3
	v_mov_b32_dpp v124, v190 row_ror:8 row_mask:0xf bank_mask:0x3
	v_mov_b32_dpp v125, v191 row_ror:8 row_mask:0xf bank_mask:0x3
	global_store_dwordx4 v154, v[126:129], s[88:89] offset:0
	global_store_dwordx4 v155, v[122:125], s[88:89] offset:0
	v_cvt_pk_bf16_f32 v176, v118, v119
	v_cvt_pk_bf16_f32 v177, v120, v121
	v_cvt_pk_bf16_f32 v178, v114, v115
	v_cvt_pk_bf16_f32 v179, v116, v117
	global_store_dwordx4 v153, v[176:179], s[86:87] offset:256
	v_mov_b32_e32 v192, v118
	v_mov_b32_e32 v193, v119
	v_mov_b32_e32 v194, v120
	v_mov_b32_e32 v195, v121
	v_mov_b32_dpp v118, v114 row_ror:8 row_mask:0xf bank_mask:0xc
	v_mov_b32_dpp v119, v115 row_ror:8 row_mask:0xf bank_mask:0xc
	v_mov_b32_dpp v120, v116 row_ror:8 row_mask:0xf bank_mask:0xc
	v_mov_b32_dpp v121, v117 row_ror:8 row_mask:0xf bank_mask:0xc
	v_mov_b32_dpp v114, v192 row_ror:8 row_mask:0xf bank_mask:0x3
	v_mov_b32_dpp v115, v193 row_ror:8 row_mask:0xf bank_mask:0x3
	v_mov_b32_dpp v116, v194 row_ror:8 row_mask:0xf bank_mask:0x3
	v_mov_b32_dpp v117, v195 row_ror:8 row_mask:0xf bank_mask:0x3
	global_store_dwordx4 v154, v[118:121], s[88:89] offset:512
	global_store_dwordx4 v155, v[114:117], s[88:89] offset:512
	s_add_u32 s86, s86, 0xc000
	s_addc_u32 s87, s87, 0
	s_add_u32 s88, s88, 0x8000
	s_addc_u32 s89, s89, 0
	v_cvt_pk_bf16_f32 v180, v110, v111
	v_cvt_pk_bf16_f32 v181, v112, v113
	v_cvt_pk_bf16_f32 v182, v106, v107
	v_cvt_pk_bf16_f32 v183, v108, v109
	global_store_dwordx4 v153, v[180:183], s[86:87] offset:0
	v_mov_b32_e32 v188, v110
	v_mov_b32_e32 v189, v111
	v_mov_b32_e32 v190, v112
	v_mov_b32_e32 v191, v113
	v_mov_b32_dpp v110, v106 row_ror:8 row_mask:0xf bank_mask:0xc
	v_mov_b32_dpp v111, v107 row_ror:8 row_mask:0xf bank_mask:0xc
	v_mov_b32_dpp v112, v108 row_ror:8 row_mask:0xf bank_mask:0xc
	v_mov_b32_dpp v113, v109 row_ror:8 row_mask:0xf bank_mask:0xc
	v_mov_b32_dpp v106, v188 row_ror:8 row_mask:0xf bank_mask:0x3
	v_mov_b32_dpp v107, v189 row_ror:8 row_mask:0xf bank_mask:0x3
	v_mov_b32_dpp v108, v190 row_ror:8 row_mask:0xf bank_mask:0x3
	v_mov_b32_dpp v109, v191 row_ror:8 row_mask:0xf bank_mask:0x3
	global_store_dwordx4 v154, v[110:113], s[88:89] offset:0
	global_store_dwordx4 v155, v[106:109], s[88:89] offset:0
	v_cvt_pk_bf16_f32 v184, v102, v103
	v_cvt_pk_bf16_f32 v185, v104, v105
	v_cvt_pk_bf16_f32 v186, v98, v99
	v_cvt_pk_bf16_f32 v187, v100, v101
	global_store_dwordx4 v153, v[184:187], s[86:87] offset:256
	v_mov_b32_e32 v192, v102
	v_mov_b32_e32 v193, v103
	v_mov_b32_e32 v194, v104
	v_mov_b32_e32 v195, v105
	v_mov_b32_dpp v102, v98 row_ror:8 row_mask:0xf bank_mask:0xc
	v_mov_b32_dpp v103, v99 row_ror:8 row_mask:0xf bank_mask:0xc
	v_mov_b32_dpp v104, v100 row_ror:8 row_mask:0xf bank_mask:0xc
	v_mov_b32_dpp v105, v101 row_ror:8 row_mask:0xf bank_mask:0xc
	v_mov_b32_dpp v98, v192 row_ror:8 row_mask:0xf bank_mask:0x3
	v_mov_b32_dpp v99, v193 row_ror:8 row_mask:0xf bank_mask:0x3
	v_mov_b32_dpp v100, v194 row_ror:8 row_mask:0xf bank_mask:0x3
	v_mov_b32_dpp v101, v195 row_ror:8 row_mask:0xf bank_mask:0x3
	global_store_dwordx4 v154, v[102:105], s[88:89] offset:512
	global_store_dwordx4 v155, v[98:101], s[88:89] offset:512
	s_add_u32 s86, s86, 0xc000
	s_addc_u32 s87, s87, 0
	s_add_u32 s88, s88, 0x8000
	s_addc_u32 s89, s89, 0
	v_cvt_pk_bf16_f32 v172, v94, v95
	v_cvt_pk_bf16_f32 v173, v96, v97
	v_cvt_pk_bf16_f32 v174, v90, v91
	v_cvt_pk_bf16_f32 v175, v92, v93
	global_store_dwordx4 v153, v[172:175], s[86:87] offset:0
	v_mov_b32_e32 v188, v94
	v_mov_b32_e32 v189, v95
	v_mov_b32_e32 v190, v96
	v_mov_b32_e32 v191, v97
	v_mov_b32_dpp v94, v90 row_ror:8 row_mask:0xf bank_mask:0xc
	v_mov_b32_dpp v95, v91 row_ror:8 row_mask:0xf bank_mask:0xc
	v_mov_b32_dpp v96, v92 row_ror:8 row_mask:0xf bank_mask:0xc
	v_mov_b32_dpp v97, v93 row_ror:8 row_mask:0xf bank_mask:0xc
	v_mov_b32_dpp v90, v188 row_ror:8 row_mask:0xf bank_mask:0x3
	v_mov_b32_dpp v91, v189 row_ror:8 row_mask:0xf bank_mask:0x3
	v_mov_b32_dpp v92, v190 row_ror:8 row_mask:0xf bank_mask:0x3
	v_mov_b32_dpp v93, v191 row_ror:8 row_mask:0xf bank_mask:0x3
	global_store_dwordx4 v154, v[94:97], s[88:89] offset:0
	global_store_dwordx4 v155, v[90:93], s[88:89] offset:0
	v_cvt_pk_bf16_f32 v176, v86, v87
	v_cvt_pk_bf16_f32 v177, v88, v89
	v_cvt_pk_bf16_f32 v178, v82, v83
	v_cvt_pk_bf16_f32 v179, v84, v85
	global_store_dwordx4 v153, v[176:179], s[86:87] offset:256
	v_mov_b32_e32 v192, v86
	v_mov_b32_e32 v193, v87
	v_mov_b32_e32 v194, v88
	v_mov_b32_e32 v195, v89
	v_mov_b32_dpp v86, v82 row_ror:8 row_mask:0xf bank_mask:0xc
	v_mov_b32_dpp v87, v83 row_ror:8 row_mask:0xf bank_mask:0xc
	v_mov_b32_dpp v88, v84 row_ror:8 row_mask:0xf bank_mask:0xc
	v_mov_b32_dpp v89, v85 row_ror:8 row_mask:0xf bank_mask:0xc
	v_mov_b32_dpp v82, v192 row_ror:8 row_mask:0xf bank_mask:0x3
	v_mov_b32_dpp v83, v193 row_ror:8 row_mask:0xf bank_mask:0x3
	v_mov_b32_dpp v84, v194 row_ror:8 row_mask:0xf bank_mask:0x3
	v_mov_b32_dpp v85, v195 row_ror:8 row_mask:0xf bank_mask:0x3
	global_store_dwordx4 v154, v[86:89], s[88:89] offset:512
	global_store_dwordx4 v155, v[82:85], s[88:89] offset:512
	s_add_u32 s86, s86, 0xc000
	s_addc_u32 s87, s87, 0
	s_add_u32 s88, s88, 0x8000
	s_addc_u32 s89, s89, 0
	v_cvt_pk_bf16_f32 v180, v78, v79
	v_cvt_pk_bf16_f32 v181, v80, v81
	v_cvt_pk_bf16_f32 v182, v74, v75
	v_cvt_pk_bf16_f32 v183, v76, v77
	global_store_dwordx4 v153, v[180:183], s[86:87] offset:0
	v_mov_b32_e32 v188, v78
	v_mov_b32_e32 v189, v79
	v_mov_b32_e32 v190, v80
	v_mov_b32_e32 v191, v81
	v_mov_b32_dpp v78, v74 row_ror:8 row_mask:0xf bank_mask:0xc
	v_mov_b32_dpp v79, v75 row_ror:8 row_mask:0xf bank_mask:0xc
	v_mov_b32_dpp v80, v76 row_ror:8 row_mask:0xf bank_mask:0xc
	v_mov_b32_dpp v81, v77 row_ror:8 row_mask:0xf bank_mask:0xc
	v_mov_b32_dpp v74, v188 row_ror:8 row_mask:0xf bank_mask:0x3
	v_mov_b32_dpp v75, v189 row_ror:8 row_mask:0xf bank_mask:0x3
	v_mov_b32_dpp v76, v190 row_ror:8 row_mask:0xf bank_mask:0x3
	v_mov_b32_dpp v77, v191 row_ror:8 row_mask:0xf bank_mask:0x3
	global_store_dwordx4 v154, v[78:81], s[88:89] offset:0
	global_store_dwordx4 v155, v[74:77], s[88:89] offset:0
	v_cvt_pk_bf16_f32 v184, v70, v71
	v_cvt_pk_bf16_f32 v185, v72, v73
	v_cvt_pk_bf16_f32 v186, v66, v67
	v_cvt_pk_bf16_f32 v187, v68, v69
	global_store_dwordx4 v153, v[184:187], s[86:87] offset:256
	v_mov_b32_e32 v192, v70
	v_mov_b32_e32 v193, v71
	v_mov_b32_e32 v194, v72
	v_mov_b32_e32 v195, v73
	v_mov_b32_dpp v70, v66 row_ror:8 row_mask:0xf bank_mask:0xc
	v_mov_b32_dpp v71, v67 row_ror:8 row_mask:0xf bank_mask:0xc
	v_mov_b32_dpp v72, v68 row_ror:8 row_mask:0xf bank_mask:0xc
	v_mov_b32_dpp v73, v69 row_ror:8 row_mask:0xf bank_mask:0xc
	v_mov_b32_dpp v66, v192 row_ror:8 row_mask:0xf bank_mask:0x3
	v_mov_b32_dpp v67, v193 row_ror:8 row_mask:0xf bank_mask:0x3
	v_mov_b32_dpp v68, v194 row_ror:8 row_mask:0xf bank_mask:0x3
	v_mov_b32_dpp v69, v195 row_ror:8 row_mask:0xf bank_mask:0x3
	global_store_dwordx4 v154, v[70:73], s[88:89] offset:512
	global_store_dwordx4 v155, v[66:69], s[88:89] offset:512
	s_branch .Lepi_done
.Lepi_pr_h:
	v_mul_u32_u24_e32 v153, 0xe00, v152
	v_lshl_add_u32 v153, v166, 1, v153
	s_add_u32 s86, s10, s46
	s_addc_u32 s87, s11, 0
	s_sub_u32 s86, s86, 0xc00
	s_subb_u32 s87, s87, 0
	s_lshl_b32 s46, s6, 10
	v_lshlrev_b32_e32 v156, 2, v166
	s_cmp_gt_i32 s84, 63
	s_cbranch_scc1 .Lepi_prs_h
	v_cvt_pk_bf16_f32 v172, v126, v127
	v_cvt_pk_bf16_f32 v173, v128, v129
	v_cvt_pk_bf16_f32 v174, v122, v123
	v_cvt_pk_bf16_f32 v175, v124, v125
	global_store_dwordx4 v153, v[172:175], s[86:87] offset:0
	v_cvt_pk_bf16_f32 v176, v118, v119
	v_cvt_pk_bf16_f32 v177, v120, v121
	v_cvt_pk_bf16_f32 v178, v114, v115
	v_cvt_pk_bf16_f32 v179, v116, v117
	global_store_dwordx4 v153, v[176:179], s[86:87] offset:256
	s_add_u32 s86, s86, 0xe000
	s_addc_u32 s87, s87, 0
	v_cvt_pk_bf16_f32 v180, v110, v111
	v_cvt_pk_bf16_f32 v181, v112, v113
	v_cvt_pk_bf16_f32 v182, v106, v107
	v_cvt_pk_bf16_f32 v183, v108, v109
	global_store_dwordx4 v153, v[180:183], s[86:87] offset:0
	v_cvt_pk_bf16_f32 v184, v102, v103
	v_cvt_pk_bf16_f32 v185, v104, v105
	v_cvt_pk_bf16_f32 v186, v98, v99
	v_cvt_pk_bf16_f32 v187, v100, v101
	global_store_dwordx4 v153, v[184:187], s[86:87] offset:256
	s_add_u32 s86, s86, 0xe000
	s_addc_u32 s87, s87, 0
	v_cvt_pk_bf16_f32 v172, v94, v95
	v_cvt_pk_bf16_f32 v173, v96, v97
	v_cvt_pk_bf16_f32 v174, v90, v91
	v_cvt_pk_bf16_f32 v175, v92, v93
	global_store_dwordx4 v153, v[172:175], s[86:87] offset:0
	v_cvt_pk_bf16_f32 v176, v86, v87
	v_cvt_pk_bf16_f32 v177, v88, v89
	v_cvt_pk_bf16_f32 v178, v82, v83
	v_cvt_pk_bf16_f32 v179, v84, v85
	global_store_dwordx4 v153, v[176:179], s[86:87] offset:256
	s_add_u32 s86, s86, 0xe000
	s_addc_u32 s87, s87, 0
	v_cvt_pk_bf16_f32 v180, v78, v79
	v_cvt_pk_bf16_f32 v181, v80, v81
	v_cvt_pk_bf16_f32 v182, v74, v75
	v_cvt_pk_bf16_f32 v183, v76, v77
	global_store_dwordx4 v153, v[180:183], s[86:87] offset:0
	v_cvt_pk_bf16_f32 v184, v70, v71
	v_cvt_pk_bf16_f32 v185, v72, v73
	v_cvt_pk_bf16_f32 v186, v66, v67
	v_cvt_pk_bf16_f32 v187, v68, v69
	global_store_dwordx4 v153, v[184:187], s[86:87] offset:256
	s_and_b32 s47, s84, 7
	s_cmp_eq_u32 s47, 7
	s_cbranch_scc0 .Lepi_done
	s_bitcmp1_b32 s98, 0
	s_cbranch_scc0 .Lepi_done
	s_and_b64 vcc, exec, s[0:1]
	s_cbranch_vccz .Lepi_done
	s_lshr_b32 s47, s84, 3
	s_mul_i32 s47, s47, 0x1c00
	s_add_i32 s47, s47, s46
	s_add_u32 s88, s20, s47
	s_addc_u32 s89, s21, 0
	s_sub_u32 s88, s88, 0x1800
	s_subb_u32 s89, s89, 0
	v_and_b32_e32 v157, 15, v164
	v_cmp_eq_u32_e32 vcc, 15, v157
	s_nop 4
	s_and_saveexec_b64 s[48:49], vcc
	global_store_dwordx4 v156, v[78:81], s[88:89] offset:0
	global_store_dwordx4 v156, v[74:77], s[88:89] offset:16
	global_store_dwordx4 v156, v[70:73], s[88:89] offset:512
	global_store_dwordx4 v156, v[66:69], s[88:89] offset:528
	s_mov_b64 exec, s[48:49]
	s_branch .Lepi_done
.Lepi_prs_h:
	v_add_u32_e32 v157, 0xffffc000, v152
	v_lshrrev_b32_e32 v157, 2, v157
	v_mul_u32_u24_e32 v157, 0x1c00, v157
	v_add_u32_e32 v156, v156, v157
	s_add_u32 s88, s36, s46
	s_addc_u32 s89, s37, 0
	s_sub_u32 s88, s88, 0x1800
	s_subb_u32 s89, s89, 0
	v_cvt_pk_bf16_f32 v172, v126, v127
	v_cvt_pk_bf16_f32 v173, v128, v129
	v_cvt_pk_bf16_f32 v174, v122, v123
	v_cvt_pk_bf16_f32 v175, v124, v125
	global_store_dwordx4 v153, v[172:175], s[86:87] offset:0
	v_cvt_pk_bf16_f32 v176, v118, v119
	v_cvt_pk_bf16_f32 v177, v120, v121
	v_cvt_pk_bf16_f32 v178, v114, v115
	v_cvt_pk_bf16_f32 v179, v116, v117
	global_store_dwordx4 v153, v[176:179], s[86:87] offset:256
	s_mov_b64 exec, s[2:3]
	global_store_dwordx4 v156, v[126:129], s[88:89] offset:0
	global_store_dwordx4 v156, v[122:125], s[88:89] offset:16
	global_store_dwordx4 v156, v[118:121], s[88:89] offset:512
	global_store_dwordx4 v156, v[114:117], s[88:89] offset:528
	s_mov_b64 exec, -1
	s_add_u32 s86, s86, 0xe000
	s_addc_u32 s87, s87, 0
	s_add_u32 s88, s88, 0x7000
	s_addc_u32 s89, s89, 0
	v_cvt_pk_bf16_f32 v180, v110, v111
	v_cvt_pk_bf16_f32 v181, v112, v113
	v_cvt_pk_bf16_f32 v182, v106, v107
	v_cvt_pk_bf16_f32 v183, v108, v109
	global_store_dwordx4 v153, v[180:183], s[86:87] offset:0
	v_cvt_pk_bf16_f32 v184, v102, v103
	v_cvt_pk_bf16_f32 v185, v104, v105
	v_cvt_pk_bf16_f32 v186, v98, v99
	v_cvt_pk_bf16_f32 v187, v100, v101
	global_store_dwordx4 v153, v[184:187], s[86:87] offset:256
	s_mov_b64 exec, s[2:3]
	global_store_dwordx4 v156, v[110:113], s[88:89] offset:0
	global_store_dwordx4 v156, v[106:109], s[88:89] offset:16
	global_store_dwordx4 v156, v[102:105], s[88:89] offset:512
	global_store_dwordx4 v156, v[98:101], s[88:89] offset:528
	s_mov_b64 exec, -1
	s_add_u32 s86, s86, 0xe000
	s_addc_u32 s87, s87, 0
	s_add_u32 s88, s88, 0x7000
	s_addc_u32 s89, s89, 0
	v_cvt_pk_bf16_f32 v172, v94, v95
	v_cvt_pk_bf16_f32 v173, v96, v97
	v_cvt_pk_bf16_f32 v174, v90, v91
	v_cvt_pk_bf16_f32 v175, v92, v93
	global_store_dwordx4 v153, v[172:175], s[86:87] offset:0
	v_cvt_pk_bf16_f32 v176, v86, v87
	v_cvt_pk_bf16_f32 v177, v88, v89
	v_cvt_pk_bf16_f32 v178, v82, v83
	v_cvt_pk_bf16_f32 v179, v84, v85
	global_store_dwordx4 v153, v[176:179], s[86:87] offset:256
	s_mov_b64 exec, s[2:3]
	global_store_dwordx4 v156, v[94:97], s[88:89] offset:0
	global_store_dwordx4 v156, v[90:93], s[88:89] offset:16
	global_store_dwordx4 v156, v[86:89], s[88:89] offset:512
	global_store_dwordx4 v156, v[82:85], s[88:89] offset:528
	s_mov_b64 exec, -1
	s_add_u32 s86, s86, 0xe000
	s_addc_u32 s87, s87, 0
	s_add_u32 s88, s88, 0x7000
	s_addc_u32 s89, s89, 0
	v_cvt_pk_bf16_f32 v180, v78, v79
	v_cvt_pk_bf16_f32 v181, v80, v81
	v_cvt_pk_bf16_f32 v182, v74, v75
	v_cvt_pk_bf16_f32 v183, v76, v77
	global_store_dwordx4 v153, v[180:183], s[86:87] offset:0
	v_cvt_pk_bf16_f32 v184, v70, v71
	v_cvt_pk_bf16_f32 v185, v72, v73
	v_cvt_pk_bf16_f32 v186, v66, v67
	v_cvt_pk_bf16_f32 v187, v68, v69
	global_store_dwordx4 v153, v[184:187], s[86:87] offset:256
	s_mov_b64 exec, s[2:3]
	global_store_dwordx4 v156, v[78:81], s[88:89] offset:0
	global_store_dwordx4 v156, v[74:77], s[88:89] offset:16
	global_store_dwordx4 v156, v[70:73], s[88:89] offset:512
	global_store_dwordx4 v156, v[66:69], s[88:89] offset:528
	s_mov_b64 exec, -1
.Lepi_done:
	s_mov_b64 s[90:91], s[42:43]
	s_andn2_b64 vcc, exec, s[4:5]
	s_mov_b64 s[4:5], -1
	s_cbranch_vccnz .LBB0_390
	s_branch .LBB0_767

.Lk4h_loop:
	ds_read_b128 v[130:133], v167
	ds_read_b128 v[152:155], v167 offset:1024
	ds_read_b128 v[156:159], v167 offset:2048
	ds_read_b128 v[160:163], v167 offset:3072
	ds_read_b128 v[172:175], v168
	ds_read_b128 v[176:179], v168 offset:1024
	ds_read_b128 v[180:183], v168 offset:2048
	ds_read_b128 v[184:187], v168 offset:3072
	s_add_u32 s50, s86, 0xfffc0080
	s_addc_u32 s51, s87, -1
	s_cmp_eq_u32 s49, 12
	s_cselect_b32 s91, s7, s51
	s_cselect_b32 s90, s23, s50
	s_cselect_b32 s89, s35, s48
	s_cselect_b32 s88, s46, s47
	v_lshl_add_u64 v[220:221], s[86:87], 0, v[144:145]
	s_add_i32 m0, s75, 0xc000
	ds_read_b128 v[188:191], v169
	ds_read_b128 v[192:195], v169 offset:1024
	ds_read_b128 v[196:199], v169 offset:2048
	ds_read_b128 v[200:203], v169 offset:3072
	ds_read_b128 v[204:207], v169 offset:4096
	ds_read_b128 v[208:211], v169 offset:5120
	ds_read_b128 v[212:215], v169 offset:6144
	ds_read_b128 v[216:219], v169 offset:7168
	global_load_lds_dwordx4 v[220:221], off
	v_lshl_add_u64 v[220:221], s[86:87], 0, v[146:147]
	s_add_i32 m0, s75, 0xe000
	s_nop 0
	global_load_lds_dwordx4 v[220:221], off
	s_waitcnt vmcnt(8)
	s_waitcnt lgkmcnt(0)
	s_barrier
	s_setprio 1
	s_waitcnt lgkmcnt(0)
	v_mfma_f32_16x16x32_bf16 v[126:129], v[130:133], v[188:191], v[126:129]
	v_mfma_f32_16x16x32_bf16 v[122:125], v[156:159], v[188:191], v[122:125]
	v_mfma_f32_16x16x32_bf16 v[110:113], v[130:133], v[196:199], v[110:113]
	v_mfma_f32_16x16x32_bf16 v[106:109], v[156:159], v[196:199], v[106:109]
	v_mfma_f32_16x16x32_bf16 v[94:97], v[130:133], v[204:207], v[94:97]
	v_mfma_f32_16x16x32_bf16 v[90:93], v[156:159], v[204:207], v[90:93]
	v_mfma_f32_16x16x32_bf16 v[78:81], v[130:133], v[212:215], v[78:81]
	v_mfma_f32_16x16x32_bf16 v[74:77], v[156:159], v[212:215], v[74:77]
	v_mfma_f32_16x16x32_bf16 v[126:129], v[152:155], v[192:195], v[126:129]
	v_mfma_f32_16x16x32_bf16 v[122:125], v[160:163], v[192:195], v[122:125]
	v_mfma_f32_16x16x32_bf16 v[110:113], v[152:155], v[200:203], v[110:113]
	v_mfma_f32_16x16x32_bf16 v[106:109], v[160:163], v[200:203], v[106:109]
	v_mfma_f32_16x16x32_bf16 v[94:97], v[152:155], v[208:211], v[94:97]
	v_mfma_f32_16x16x32_bf16 v[90:93], v[160:163], v[208:211], v[90:93]
	v_mfma_f32_16x16x32_bf16 v[78:81], v[152:155], v[216:219], v[78:81]
	v_mfma_f32_16x16x32_bf16 v[74:77], v[160:163], v[216:219], v[74:77]
	s_setprio 0
	s_setprio 1
	v_mfma_f32_16x16x32_bf16 v[118:121], v[172:175], v[188:191], v[118:121]
	v_mfma_f32_16x16x32_bf16 v[114:117], v[180:183], v[188:191], v[114:117]
	v_mfma_f32_16x16x32_bf16 v[102:105], v[172:175], v[196:199], v[102:105]
	v_mfma_f32_16x16x32_bf16 v[98:101], v[180:183], v[196:199], v[98:101]
	v_mfma_f32_16x16x32_bf16 v[86:89], v[172:175], v[204:207], v[86:89]
	v_mfma_f32_16x16x32_bf16 v[82:85], v[180:183], v[204:207], v[82:85]
	v_mfma_f32_16x16x32_bf16 v[70:73], v[172:175], v[212:215], v[70:73]
	v_mfma_f32_16x16x32_bf16 v[66:69], v[180:183], v[212:215], v[66:69]
	v_mfma_f32_16x16x32_bf16 v[118:121], v[176:179], v[192:195], v[118:121]
	v_mfma_f32_16x16x32_bf16 v[114:117], v[184:187], v[192:195], v[114:117]
	v_mfma_f32_16x16x32_bf16 v[102:105], v[176:179], v[200:203], v[102:105]
	v_mfma_f32_16x16x32_bf16 v[98:101], v[184:187], v[200:203], v[98:101]
	v_mfma_f32_16x16x32_bf16 v[86:89], v[176:179], v[208:211], v[86:89]
	v_mfma_f32_16x16x32_bf16 v[82:85], v[184:187], v[208:211], v[82:85]
	v_mfma_f32_16x16x32_bf16 v[70:73], v[176:179], v[216:219], v[70:73]
	v_mfma_f32_16x16x32_bf16 v[66:69], v[184:187], v[216:219], v[66:69]
	s_setprio 0
	s_barrier
	s_add_i32 s50, s68, s74
	v_lshl_add_u64 v[220:221], s[88:89], 0, v[136:137]
	s_mov_b32 m0, s50
	global_load_lds_dwordx4 v[220:221], off
	s_add_i32 m0, s50, 0x2000
	s_add_u32 s50, s88, 0x40000
	v_lshl_add_u64 v[222:223], s[88:89], 0, v[140:141]
	s_addc_u32 s51, s89, 0
	s_add_i32 s85, s28, s74
	global_load_lds_dwordx4 v[222:223], off
	v_lshl_add_u64 v[224:225], s[50:51], 0, v[136:137]
	s_mov_b32 m0, s85
	v_lshl_add_u64 v[226:227], s[90:91], 0, v[138:139]
	global_load_lds_dwordx4 v[224:225], off
	v_lshl_add_u64 v[224:225], s[50:51], 0, v[140:141]
	s_add_i32 m0, s85, 0x2000
	s_nop 0
	global_load_lds_dwordx4 v[224:225], off
	v_lshl_add_u64 v[224:225], s[90:91], 0, v[134:135]
	s_mov_b32 m0, s75
	s_nop 0
	global_load_lds_dwordx4 v[224:225], off
	s_mov_b32 m0, s76
	s_nop 0
	global_load_lds_dwordx4 v[226:227], off
	s_waitcnt vmcnt(8)
	s_waitcnt lgkmcnt(0)
	s_barrier
	s_setprio 1
	s_waitcnt lgkmcnt(0)
	s_setprio 0
	s_setprio 1
	s_setprio 0
	s_barrier
	s_add_i32 s85, 0, 0x18000
	v_add_u32_e32 v142, s85, v165
	s_add_i32 s92, 0, 0x1c000
	ds_read_b128 v[130:133], v142
	ds_read_b128 v[152:155], v142 offset:1024
	ds_read_b128 v[156:159], v142 offset:2048
	ds_read_b128 v[160:163], v142 offset:3072
	v_add_u32_e32 v142, s92, v165
	ds_read_b128 v[172:175], v142
	ds_read_b128 v[176:179], v142 offset:1024
	ds_read_b128 v[180:183], v142 offset:2048
	ds_read_b128 v[184:187], v142 offset:3072
	s_add_u32 s50, s90, 0x40000
	s_addc_u32 s51, s91, 0
	s_mov_b32 m0, s77
	v_lshl_add_u64 v[228:229], s[50:51], 0, v[134:135]
	ds_read_b128 v[188:191], v169 offset:32768
	ds_read_b128 v[192:195], v169 offset:33792
	ds_read_b128 v[196:199], v169 offset:34816
	ds_read_b128 v[200:203], v169 offset:35840
	ds_read_b128 v[204:207], v169 offset:36864
	ds_read_b128 v[208:211], v169 offset:37888
	ds_read_b128 v[212:215], v169 offset:38912
	ds_read_b128 v[216:219], v169 offset:39936
	global_load_lds_dwordx4 v[228:229], off
	v_lshl_add_u64 v[228:229], s[50:51], 0, v[138:139]
	s_mov_b32 m0, s78
	s_nop 0
	global_load_lds_dwordx4 v[228:229], off
	s_waitcnt vmcnt(8)
	s_waitcnt lgkmcnt(0)
	s_barrier
	s_setprio 1
	s_waitcnt lgkmcnt(0)
	v_mfma_f32_16x16x32_bf16 v[126:129], v[130:133], v[188:191], v[126:129]
	v_mfma_f32_16x16x32_bf16 v[122:125], v[156:159], v[188:191], v[122:125]
	v_mfma_f32_16x16x32_bf16 v[110:113], v[130:133], v[196:199], v[110:113]
	v_mfma_f32_16x16x32_bf16 v[106:109], v[156:159], v[196:199], v[106:109]
	v_mfma_f32_16x16x32_bf16 v[94:97], v[130:133], v[204:207], v[94:97]
	v_mfma_f32_16x16x32_bf16 v[90:93], v[156:159], v[204:207], v[90:93]
	v_mfma_f32_16x16x32_bf16 v[78:81], v[130:133], v[212:215], v[78:81]
	v_mfma_f32_16x16x32_bf16 v[74:77], v[156:159], v[212:215], v[74:77]
	v_mfma_f32_16x16x32_bf16 v[126:129], v[152:155], v[192:195], v[126:129]
	v_mfma_f32_16x16x32_bf16 v[122:125], v[160:163], v[192:195], v[122:125]
	v_mfma_f32_16x16x32_bf16 v[110:113], v[152:155], v[200:203], v[110:113]
	v_mfma_f32_16x16x32_bf16 v[106:109], v[160:163], v[200:203], v[106:109]
	v_mfma_f32_16x16x32_bf16 v[94:97], v[152:155], v[208:211], v[94:97]
	v_mfma_f32_16x16x32_bf16 v[90:93], v[160:163], v[208:211], v[90:93]
	v_mfma_f32_16x16x32_bf16 v[78:81], v[152:155], v[216:219], v[78:81]
	v_mfma_f32_16x16x32_bf16 v[74:77], v[160:163], v[216:219], v[74:77]
	s_setprio 0
	s_setprio 1
	v_mfma_f32_16x16x32_bf16 v[118:121], v[172:175], v[188:191], v[118:121]
	v_mfma_f32_16x16x32_bf16 v[114:117], v[180:183], v[188:191], v[114:117]
	v_mfma_f32_16x16x32_bf16 v[102:105], v[172:175], v[196:199], v[102:105]
	v_mfma_f32_16x16x32_bf16 v[98:101], v[180:183], v[196:199], v[98:101]
	v_mfma_f32_16x16x32_bf16 v[86:89], v[172:175], v[204:207], v[86:89]
	v_mfma_f32_16x16x32_bf16 v[82:85], v[180:183], v[204:207], v[82:85]
	v_mfma_f32_16x16x32_bf16 v[70:73], v[172:175], v[212:215], v[70:73]
	v_mfma_f32_16x16x32_bf16 v[66:69], v[180:183], v[212:215], v[66:69]
	v_mfma_f32_16x16x32_bf16 v[118:121], v[176:179], v[192:195], v[118:121]
	v_mfma_f32_16x16x32_bf16 v[114:117], v[184:187], v[192:195], v[114:117]
	v_mfma_f32_16x16x32_bf16 v[102:105], v[176:179], v[200:203], v[102:105]
	v_mfma_f32_16x16x32_bf16 v[98:101], v[184:187], v[200:203], v[98:101]
	v_mfma_f32_16x16x32_bf16 v[86:89], v[176:179], v[208:211], v[86:89]
	v_mfma_f32_16x16x32_bf16 v[82:85], v[184:187], v[208:211], v[82:85]
	v_mfma_f32_16x16x32_bf16 v[70:73], v[176:179], v[216:219], v[70:73]
	v_mfma_f32_16x16x32_bf16 v[66:69], v[184:187], v[216:219], v[66:69]
	s_setprio 0
	s_barrier
	s_add_i32 s50, s85, s74
	v_lshl_add_u64 v[220:221], v[220:221], 0, s[38:39]
	s_mov_b32 m0, s50
	global_load_lds_dwordx4 v[220:221], off
	s_add_i32 m0, s50, 0x2000
	s_add_u32 s50, s88, 0x40080
	v_lshl_add_u64 v[220:221], v[222:223], 0, s[38:39]
	s_addc_u32 s51, s89, 0
	s_add_i32 s85, s92, s74
	global_load_lds_dwordx4 v[220:221], off
	v_lshl_add_u64 v[220:221], s[50:51], 0, v[136:137]
	s_mov_b32 m0, s85
	s_nop 0
	global_load_lds_dwordx4 v[220:221], off
	v_lshl_add_u64 v[220:221], s[50:51], 0, v[140:141]
	s_add_i32 m0, s85, 0x2000
	s_nop 0
	global_load_lds_dwordx4 v[220:221], off
	v_lshl_add_u64 v[220:221], v[224:225], 0, s[38:39]
	s_mov_b32 m0, s25
	s_nop 0
	global_load_lds_dwordx4 v[220:221], off
	v_lshl_add_u64 v[220:221], v[226:227], 0, s[38:39]
	s_mov_b32 m0, s69
	s_nop 0
	global_load_lds_dwordx4 v[220:221], off
	s_waitcnt vmcnt(8)
	s_waitcnt lgkmcnt(0)
	s_barrier
	s_setprio 1
	s_waitcnt lgkmcnt(0)
	s_setprio 0
	s_setprio 1
	s_setprio 0
	s_barrier
	s_add_i32 s49, s49, 2
	s_add_u32 s86, s86, 0x100
	s_addc_u32 s87, s87, 0
	s_add_u32 s47, s47, 0x100
	s_addc_u32 s48, s48, 0
	s_cmp_gt_u32 s49, 13
	s_cbranch_scc0 .Lk4h_loop
	s_branch .Lk4_after

.LBB0_774:
	s_abs_i32 s0, s33
	v_cvt_f32_u32_e32 v2, s0
	s_sub_i32 s1, 0, s0
	v_rcp_iflag_f32_e32 v2, v2
	s_nop 0
	v_mul_f32_e32 v2, 0x4f7ffffe, v2
	v_cvt_u32_f32_e32 v2, v2
	s_nop 0
	v_readfirstlane_b32 s2, v2
	s_mul_i32 s1, s1, s2
	s_mul_hi_u32 s1, s2, s1
	s_add_i32 s2, s2, s1
	s_mul_hi_u32 s1, s2, 0x35a
	s_mul_i32 s1, s1, s0
	s_sub_i32 s1, 0x35a, s1
	s_sub_i32 s2, s1, s0
	s_cmp_ge_u32 s1, s0
	s_cselect_b32 s1, s2, s1
	s_sub_i32 s2, s1, s0
	s_cmp_ge_u32 s1, s0
	s_cselect_b32 s0, s2, s1
	s_movk_i32 s0, 180
	s_cmp_ge_i32 s24, s0
	s_cbranch_scc0 .LBB0_796
	s_sub_i32 s1, s24, s0
	s_lshl_b32 s1, s1, 3
	s_add_i32 s6, s1, s83
	s_cmpk_gt_u32 s6, 0x127f
	s_cbranch_scc1 .LBB0_796
	s_sub_i32 s7, s33, s0
	s_lshl_b32 s7, s7, 3
	v_mbcnt_lo_u32_b32 v1, -1, 0
	v_mbcnt_hi_u32_b32 v1, -1, v1
	v_and_b32_e32 v2, 31, v1
	v_lshrrev_b32_e32 v3, 5, v1
	s_lshl_b32 s4, s83, 14
	v_mad_u32_u24 v4, v3, 33, v2
	v_lshl_add_u32 v4, v4, 2, s4
	v_and_b32_e32 v5, 7, v1
	v_lshrrev_b32_e32 v6, 3, v1
	v_mul_u32_u24_e32 v7, 0x108, v5
	v_add_u32_e32 v7, v7, v6
	v_lshl_add_u32 v7, v7, 2, s4
